# scan consumer chunk boundary: stage-buffer addresses toggled with XOR (7 header instructions instead of 13, all in DPP gaps), three loads of the next chunk issued inside the last step
# speedup vs baseline: 1.0064x; 1.0051x over previous
; #define LAS __attribute__((address_space(3)))
; #define RW_LDS_WAIT(X) asm volatile("s_waitcnt lgkmcnt(0)" : "+v"(nk##X), "+v"(dd##X), "+v"(bb##X), "+v"(kp##X), "+v"(rr##X), "+v"(vv##X) :: "memory")
; DI void rwkv_scan_phase(int wv, const Params& P, LAS unsigned char* lds) {
;     ...
;         } else {
;             const int cg = lane & 15, rloc = wave * 4 + (lane >> 4);
;             f32x4 S = (f32x4){0.f, 0.f, 0.f, 0.f};
;             __syncthreads();
;             __builtin_amdgcn_s_setprio(3);
; #pragma unroll 1
;             for (int ck = 0; ck < nck; ++ck) { const int buf = ck & 1;
;                 const LAS float* sb = stg + buf * RW_T * 5 * 64 + 4 * cg; const LAS float* vb = vst + buf * RW_T * 8 + rloc; LAS float* yb = ybuf + buf * RW_T * 128 + wave * 64 + lane;
;                 const unsigned sba = (unsigned)(size_t)sb, vba = (unsigned)(size_t)vb;
;                 f32x4 nkA, ddA, bbA, kpA, rrA, nkB, ddB, bbB, kpB, rrB; float vvA, vvB;
;     ...
;                 f32x2 yacc = (f32x2){0.f, 0.f};
;                 unsigned sbt = sba, vbt = vba; LAS float* ybt = yb;
;                 RW_LDS_LOAD(A, 0); RW_LDS_WAIT(A);
; #pragma unroll 1
;                 for (int tt = 0; tt < RW_T; tt += 16) { sbt = sba + (unsigned)tt * 1280u; vbt = vba + (unsigned)tt * 32u; ybt = yb + tt * 128;
;                     RW_LDS_LOAD(B, 1); RW_STEP(A, 0); RW_LDS_WAIT(B);
;                     RW_LDS_LOAD(A, 2); RW_STEP(B, 1); RW_LDS_WAIT(A);
.LBB0_3177:
	s_waitcnt lgkmcnt(0)
	s_barrier
	s_and_saveexec_b64 s[20:21], s[2:3]
	s_xor_b64 s[20:21], exec, s[20:21]
	s_cbranch_execz .LBB0_3185
	s_barrier
	s_setprio 3
	v_add_u32_e32 v42, 0xfffec000, v63
	v_mov_b32_e32 v58, 0
	v_mov_b32_e32 v59, 0
	v_lshl_add_u32 v42, v42, 6, v45
	v_mov_b32_e32 v60, 0
	v_mov_b32_e32 v61, 0
	v_add_u32_e32 v42, 0x400, v42
	v_add_u32_e32 v62, 0x3800, v66
	s_mov_b32 s47, 0
	s_mov_b32 s42, 0
	v_mov_b32_e32 v74, v45
	v_mov_b32_e32 v75, v42
	v_add_u32_e32 v67, s42, v62
	v_add_u32_e32 v72, 0x4000, v62
	ds_read_b128 v[20:23], v74 offset:3072
	ds_read_b128 v[36:39], v74 offset:3328
	ds_read_b128 v[24:27], v74 offset:3584
	ds_read_b128 v[0:3], v74
	ds_read_b128 v[16:19], v74 offset:256
	ds_read_b128 v[4:7], v74 offset:512
	ds_read_b128 v[12:15], v75
	ds_read_b128 v[8:11], v74 offset:768
	ds_read_b128 v[32:35], v75 offset:3072
	ds_read_b128 v[28:31], v74 offset:3840
.Lscan_chunk:
	s_waitcnt lgkmcnt(2)
	v_pk_mul_f32 v[0:1], v[58:59], v[0:1] op_sel_hi:[0,1]
	v_pk_fma_f32 v[0:1], v[58:59], v[2:3], v[0:1] op_sel:[1,0,0] op_sel_hi:[1,1,1]
	v_pk_fma_f32 v[0:1], v[60:61], v[16:17], v[0:1] op_sel_hi:[0,1,1]
	v_pk_fma_f32 v[0:1], v[60:61], v[18:19], v[0:1] op_sel:[1,0,0] op_sel_hi:[1,1,1]
	v_pk_fma_f32 v[12:13], v[58:59], v[4:5], v[12:13]
	v_pk_fma_f32 v[14:15], v[60:61], v[6:7], v[14:15]
	v_add_f32_dpp v0, v0, v0 quad_perm:[1,0,3,2] row_mask:0xf bank_mask:0xf bound_ctrl:1
	ds_read_b128 v[46:49], v74 offset:6144
	ds_read_b128 v[76:79], v74 offset:6400
	v_add_f32_dpp v0, v0, v0 quad_perm:[2,3,0,1] row_mask:0xf bank_mask:0xf bound_ctrl:1
	ds_read_b128 v[50:53], v74 offset:6656
	ds_read_b128 v[68:71], v75 offset:6144
	v_add_f32_dpp v0, v0, v0 row_half_mirror row_mask:0xf bank_mask:0xf bound_ctrl:1
	ds_read_b128 v[54:57], v74 offset:6912
	ds_write_b32 v72, v1 offset:7680
	v_add_f32_dpp v0, v0, v0 row_mirror row_mask:0xf bank_mask:0xf bound_ctrl:1
	v_pk_fma_f32 v[58:59], v[8:9], v[0:1], v[12:13] op_sel_hi:[1,0,1]
	v_pk_fma_f32 v[60:61], v[10:11], v[0:1], v[14:15] op_sel_hi:[1,0,1]
	v_mov_b32_e32 v72, v67
	s_waitcnt lgkmcnt(6)
	v_pk_mul_f32 v[20:21], v[58:59], v[20:21] op_sel_hi:[0,1]
	v_pk_fma_f32 v[20:21], v[58:59], v[22:23], v[20:21] op_sel:[1,0,0] op_sel_hi:[1,1,1]
	v_pk_fma_f32 v[20:21], v[60:61], v[36:37], v[20:21] op_sel_hi:[0,1,1]
	v_pk_fma_f32 v[20:21], v[60:61], v[38:39], v[20:21] op_sel:[1,0,0] op_sel_hi:[1,1,1]
	v_pk_fma_f32 v[32:33], v[58:59], v[24:25], v[32:33]
	v_pk_fma_f32 v[34:35], v[60:61], v[26:27], v[34:35]
	v_add_f32_dpp v20, v20, v20 quad_perm:[1,0,3,2] row_mask:0xf bank_mask:0xf bound_ctrl:1
	ds_read_b128 v[0:3], v74 offset:9216
	ds_read_b128 v[16:19], v74 offset:9472
	v_add_f32_dpp v20, v20, v20 quad_perm:[2,3,0,1] row_mask:0xf bank_mask:0xf bound_ctrl:1
	ds_read_b128 v[4:7], v74 offset:9728
	ds_read_b128 v[12:15], v75 offset:9216
	v_add_f32_dpp v20, v20, v20 row_half_mirror row_mask:0xf bank_mask:0xf bound_ctrl:1
	ds_read_b128 v[8:11], v74 offset:9984
	ds_write_b32 v72, v21
	v_add_f32_dpp v20, v20, v20 row_mirror row_mask:0xf bank_mask:0xf bound_ctrl:1
	v_pk_fma_f32 v[58:59], v[28:29], v[20:21], v[32:33] op_sel_hi:[1,0,1]
	v_pk_fma_f32 v[60:61], v[30:31], v[20:21], v[34:35] op_sel_hi:[1,0,1]
	s_waitcnt lgkmcnt(7)
	v_pk_mul_f32 v[46:47], v[58:59], v[46:47] op_sel_hi:[0,1]
	v_pk_fma_f32 v[46:47], v[58:59], v[48:49], v[46:47] op_sel:[1,0,0] op_sel_hi:[1,1,1]
	v_pk_fma_f32 v[46:47], v[60:61], v[76:77], v[46:47] op_sel_hi:[0,1,1]
	v_pk_fma_f32 v[46:47], v[60:61], v[78:79], v[46:47] op_sel:[1,0,0] op_sel_hi:[1,1,1]
	v_pk_fma_f32 v[68:69], v[58:59], v[50:51], v[68:69]
	v_pk_fma_f32 v[70:71], v[60:61], v[52:53], v[70:71]
	v_add_f32_dpp v46, v46, v46 quad_perm:[1,0,3,2] row_mask:0xf bank_mask:0xf bound_ctrl:1
	ds_read_b128 v[20:23], v74 offset:12288
	ds_read_b128 v[36:39], v74 offset:12544
	v_add_f32_dpp v46, v46, v46 quad_perm:[2,3,0,1] row_mask:0xf bank_mask:0xf bound_ctrl:1
	ds_read_b128 v[24:27], v74 offset:12800
	ds_read_b128 v[32:35], v75 offset:12288
	v_add_f32_dpp v46, v46, v46 row_half_mirror row_mask:0xf bank_mask:0xf bound_ctrl:1
	ds_read_b128 v[28:31], v74 offset:13056
	ds_write_b32 v72, v47 offset:512
	v_add_f32_dpp v46, v46, v46 row_mirror row_mask:0xf bank_mask:0xf bound_ctrl:1
	v_pk_fma_f32 v[58:59], v[54:55], v[46:47], v[68:69] op_sel_hi:[1,0,1]
	v_pk_fma_f32 v[60:61], v[56:57], v[46:47], v[70:71] op_sel_hi:[1,0,1]
	s_waitcnt lgkmcnt(7)
	v_pk_mul_f32 v[0:1], v[58:59], v[0:1] op_sel_hi:[0,1]
	v_pk_fma_f32 v[0:1], v[58:59], v[2:3], v[0:1] op_sel:[1,0,0] op_sel_hi:[1,1,1]
	v_pk_fma_f32 v[0:1], v[60:61], v[16:17], v[0:1] op_sel_hi:[0,1,1]
	v_pk_fma_f32 v[0:1], v[60:61], v[18:19], v[0:1] op_sel:[1,0,0] op_sel_hi:[1,1,1]
	v_pk_fma_f32 v[12:13], v[58:59], v[4:5], v[12:13]
	v_pk_fma_f32 v[14:15], v[60:61], v[6:7], v[14:15]
	v_add_f32_dpp v0, v0, v0 quad_perm:[1,0,3,2] row_mask:0xf bank_mask:0xf bound_ctrl:1
	ds_read_b128 v[46:49], v74 offset:15360
	ds_read_b128 v[76:79], v74 offset:15616
	v_add_f32_dpp v0, v0, v0 quad_perm:[2,3,0,1] row_mask:0xf bank_mask:0xf bound_ctrl:1
	ds_read_b128 v[50:53], v74 offset:15872
	ds_read_b128 v[68:71], v75 offset:15360
	v_add_f32_dpp v0, v0, v0 row_half_mirror row_mask:0xf bank_mask:0xf bound_ctrl:1
	ds_read_b128 v[54:57], v74 offset:16128
	ds_write_b32 v72, v1 offset:1024
	v_add_f32_dpp v0, v0, v0 row_mirror row_mask:0xf bank_mask:0xf bound_ctrl:1
	v_pk_fma_f32 v[58:59], v[8:9], v[0:1], v[12:13] op_sel_hi:[1,0,1]
	v_pk_fma_f32 v[60:61], v[10:11], v[0:1], v[14:15] op_sel_hi:[1,0,1]
	s_waitcnt lgkmcnt(7)
; #define LAS __attribute__((address_space(3)))
; #define RW_LDS_WAIT(X) asm volatile("s_waitcnt lgkmcnt(0)" : "+v"(nk##X), "+v"(dd##X), "+v"(bb##X), "+v"(kp##X), "+v"(rr##X), "+v"(vv##X) :: "memory")
; DI void rwkv_scan_phase(int wv, const Params& P, LAS unsigned char* lds) {
;     ...
;                 f32x2 yacc = (f32x2){0.f, 0.f};
;                 unsigned sbt = sba, vbt = vba; LAS float* ybt = yb;
;                 RW_LDS_LOAD(A, 0); RW_LDS_WAIT(A);
; #pragma unroll 1
;                 for (int tt = 0; tt < RW_T; tt += 16) { sbt = sba + (unsigned)tt * 1280u; vbt = vba + (unsigned)tt * 32u; ybt = yb + tt * 128;
;                     RW_LDS_LOAD(B, 1); RW_STEP(A, 0); RW_LDS_WAIT(B);
;                     RW_LDS_LOAD(A, 2); RW_STEP(B, 1); RW_LDS_WAIT(A);
;                     RW_LDS_LOAD(B, 3); RW_STEP(A, 2); RW_LDS_WAIT(B);
;                     RW_LDS_LOAD(A, 4); RW_STEP(B, 3); RW_LDS_WAIT(A);
;                     RW_LDS_LOAD(B, 5); RW_STEP(A, 4); RW_LDS_WAIT(B);
;                     RW_LDS_LOAD(A, 6); RW_STEP(B, 5); RW_LDS_WAIT(A);
;                     RW_LDS_LOAD(B, 7); RW_STEP(A, 6); RW_LDS_WAIT(B);
;                     RW_LDS_LOAD(A, 8); RW_STEP(B, 7); RW_LDS_WAIT(A);
;                     RW_LDS_LOAD(B, 9); RW_STEP(A, 8); RW_LDS_WAIT(B);
;                     RW_LDS_LOAD(A, 10); RW_STEP(B, 9); RW_LDS_WAIT(A);
;                     RW_LDS_LOAD(B, 11); RW_STEP(A, 10); RW_LDS_WAIT(B);
;                     RW_LDS_LOAD(A, 12); RW_STEP(B, 11); RW_LDS_WAIT(A);
;                     RW_LDS_LOAD(B, 13); RW_STEP(A, 12); RW_LDS_WAIT(B);
;                     RW_LDS_LOAD(A, 14); RW_STEP(B, 13); RW_LDS_WAIT(A);
;                     RW_LDS_LOAD(B, 15); RW_STEP(A, 14); RW_LDS_WAIT(B);
;                     RW_LDS_LOAD(A, 16); RW_STEP(B, 15); RW_LDS_WAIT(A);
	v_pk_mul_f32 v[20:21], v[58:59], v[20:21] op_sel_hi:[0,1]
	v_pk_fma_f32 v[20:21], v[58:59], v[22:23], v[20:21] op_sel:[1,0,0] op_sel_hi:[1,1,1]
	v_pk_fma_f32 v[20:21], v[60:61], v[36:37], v[20:21] op_sel_hi:[0,1,1]
	v_pk_fma_f32 v[20:21], v[60:61], v[38:39], v[20:21] op_sel:[1,0,0] op_sel_hi:[1,1,1]
	v_pk_fma_f32 v[32:33], v[58:59], v[24:25], v[32:33]
	v_pk_fma_f32 v[34:35], v[60:61], v[26:27], v[34:35]
	v_add_f32_dpp v20, v20, v20 quad_perm:[1,0,3,2] row_mask:0xf bank_mask:0xf bound_ctrl:1
	ds_read_b128 v[0:3], v74 offset:18432
	ds_read_b128 v[16:19], v74 offset:18688
	v_add_f32_dpp v20, v20, v20 quad_perm:[2,3,0,1] row_mask:0xf bank_mask:0xf bound_ctrl:1
	ds_read_b128 v[4:7], v74 offset:18944
	ds_read_b128 v[12:15], v75 offset:18432
	v_add_f32_dpp v20, v20, v20 row_half_mirror row_mask:0xf bank_mask:0xf bound_ctrl:1
	ds_read_b128 v[8:11], v74 offset:19200
	ds_write_b32 v72, v21 offset:1536
	v_add_f32_dpp v20, v20, v20 row_mirror row_mask:0xf bank_mask:0xf bound_ctrl:1
	v_pk_fma_f32 v[58:59], v[28:29], v[20:21], v[32:33] op_sel_hi:[1,0,1]
	v_pk_fma_f32 v[60:61], v[30:31], v[20:21], v[34:35] op_sel_hi:[1,0,1]
	s_waitcnt lgkmcnt(7)
	v_pk_mul_f32 v[46:47], v[58:59], v[46:47] op_sel_hi:[0,1]
	v_pk_fma_f32 v[46:47], v[58:59], v[48:49], v[46:47] op_sel:[1,0,0] op_sel_hi:[1,1,1]
	v_pk_fma_f32 v[46:47], v[60:61], v[76:77], v[46:47] op_sel_hi:[0,1,1]
	v_pk_fma_f32 v[46:47], v[60:61], v[78:79], v[46:47] op_sel:[1,0,0] op_sel_hi:[1,1,1]
	v_pk_fma_f32 v[68:69], v[58:59], v[50:51], v[68:69]
	v_pk_fma_f32 v[70:71], v[60:61], v[52:53], v[70:71]
	v_add_f32_dpp v46, v46, v46 quad_perm:[1,0,3,2] row_mask:0xf bank_mask:0xf bound_ctrl:1
	ds_read_b128 v[20:23], v74 offset:21504
	ds_read_b128 v[36:39], v74 offset:21760
	v_add_f32_dpp v46, v46, v46 quad_perm:[2,3,0,1] row_mask:0xf bank_mask:0xf bound_ctrl:1
	ds_read_b128 v[24:27], v74 offset:22016
	ds_read_b128 v[32:35], v75 offset:21504
	v_add_f32_dpp v46, v46, v46 row_half_mirror row_mask:0xf bank_mask:0xf bound_ctrl:1
	ds_read_b128 v[28:31], v74 offset:22272
	ds_write_b32 v72, v47 offset:2048
	v_add_f32_dpp v46, v46, v46 row_mirror row_mask:0xf bank_mask:0xf bound_ctrl:1
	v_pk_fma_f32 v[58:59], v[54:55], v[46:47], v[68:69] op_sel_hi:[1,0,1]
	v_pk_fma_f32 v[60:61], v[56:57], v[46:47], v[70:71] op_sel_hi:[1,0,1]
	s_waitcnt lgkmcnt(7)
	v_pk_mul_f32 v[0:1], v[58:59], v[0:1] op_sel_hi:[0,1]
	v_pk_fma_f32 v[0:1], v[58:59], v[2:3], v[0:1] op_sel:[1,0,0] op_sel_hi:[1,1,1]
	v_pk_fma_f32 v[0:1], v[60:61], v[16:17], v[0:1] op_sel_hi:[0,1,1]
	v_pk_fma_f32 v[0:1], v[60:61], v[18:19], v[0:1] op_sel:[1,0,0] op_sel_hi:[1,1,1]
	v_pk_fma_f32 v[12:13], v[58:59], v[4:5], v[12:13]
	v_pk_fma_f32 v[14:15], v[60:61], v[6:7], v[14:15]
	v_add_f32_dpp v0, v0, v0 quad_perm:[1,0,3,2] row_mask:0xf bank_mask:0xf bound_ctrl:1
	ds_read_b128 v[46:49], v74 offset:24576
	ds_read_b128 v[76:79], v74 offset:24832
	v_add_f32_dpp v0, v0, v0 quad_perm:[2,3,0,1] row_mask:0xf bank_mask:0xf bound_ctrl:1
	ds_read_b128 v[50:53], v74 offset:25088
	ds_read_b128 v[68:71], v75 offset:24576
	v_add_f32_dpp v0, v0, v0 row_half_mirror row_mask:0xf bank_mask:0xf bound_ctrl:1
	ds_read_b128 v[54:57], v74 offset:25344
	ds_write_b32 v72, v1 offset:2560
	v_add_f32_dpp v0, v0, v0 row_mirror row_mask:0xf bank_mask:0xf bound_ctrl:1
	v_pk_fma_f32 v[58:59], v[8:9], v[0:1], v[12:13] op_sel_hi:[1,0,1]
	v_pk_fma_f32 v[60:61], v[10:11], v[0:1], v[14:15] op_sel_hi:[1,0,1]
	s_waitcnt lgkmcnt(7)
	v_pk_mul_f32 v[20:21], v[58:59], v[20:21] op_sel_hi:[0,1]
	v_pk_fma_f32 v[20:21], v[58:59], v[22:23], v[20:21] op_sel:[1,0,0] op_sel_hi:[1,1,1]
	v_pk_fma_f32 v[20:21], v[60:61], v[36:37], v[20:21] op_sel_hi:[0,1,1]
	v_pk_fma_f32 v[20:21], v[60:61], v[38:39], v[20:21] op_sel:[1,0,0] op_sel_hi:[1,1,1]
	v_pk_fma_f32 v[32:33], v[58:59], v[24:25], v[32:33]
	v_pk_fma_f32 v[34:35], v[60:61], v[26:27], v[34:35]
	v_add_f32_dpp v20, v20, v20 quad_perm:[1,0,3,2] row_mask:0xf bank_mask:0xf bound_ctrl:1
	ds_read_b128 v[0:3], v74 offset:27648
	ds_read_b128 v[16:19], v74 offset:27904
	v_add_f32_dpp v20, v20, v20 quad_perm:[2,3,0,1] row_mask:0xf bank_mask:0xf bound_ctrl:1
	ds_read_b128 v[4:7], v74 offset:28160
	ds_read_b128 v[12:15], v75 offset:27648
	v_add_f32_dpp v20, v20, v20 row_half_mirror row_mask:0xf bank_mask:0xf bound_ctrl:1
	ds_read_b128 v[8:11], v74 offset:28416
	ds_write_b32 v72, v21 offset:3072
	v_add_f32_dpp v20, v20, v20 row_mirror row_mask:0xf bank_mask:0xf bound_ctrl:1
	v_pk_fma_f32 v[58:59], v[28:29], v[20:21], v[32:33] op_sel_hi:[1,0,1]
	v_pk_fma_f32 v[60:61], v[30:31], v[20:21], v[34:35] op_sel_hi:[1,0,1]
	s_waitcnt lgkmcnt(7)
	v_pk_mul_f32 v[46:47], v[58:59], v[46:47] op_sel_hi:[0,1]
	v_pk_fma_f32 v[46:47], v[58:59], v[48:49], v[46:47] op_sel:[1,0,0] op_sel_hi:[1,1,1]
	v_pk_fma_f32 v[46:47], v[60:61], v[76:77], v[46:47] op_sel_hi:[0,1,1]
	v_pk_fma_f32 v[46:47], v[60:61], v[78:79], v[46:47] op_sel:[1,0,0] op_sel_hi:[1,1,1]
	v_pk_fma_f32 v[68:69], v[58:59], v[50:51], v[68:69]
	v_pk_fma_f32 v[70:71], v[60:61], v[52:53], v[70:71]
	v_add_f32_dpp v46, v46, v46 quad_perm:[1,0,3,2] row_mask:0xf bank_mask:0xf bound_ctrl:1
	ds_read_b128 v[20:23], v74 offset:30720
	ds_read_b128 v[36:39], v74 offset:30976
	v_add_f32_dpp v46, v46, v46 quad_perm:[2,3,0,1] row_mask:0xf bank_mask:0xf bound_ctrl:1
	ds_read_b128 v[24:27], v74 offset:31232
	ds_read_b128 v[32:35], v75 offset:30720
	v_add_f32_dpp v46, v46, v46 row_half_mirror row_mask:0xf bank_mask:0xf bound_ctrl:1
	ds_read_b128 v[28:31], v74 offset:31488
	ds_write_b32 v72, v47 offset:3584
	v_add_f32_dpp v46, v46, v46 row_mirror row_mask:0xf bank_mask:0xf bound_ctrl:1
	v_pk_fma_f32 v[58:59], v[54:55], v[46:47], v[68:69] op_sel_hi:[1,0,1]
	v_pk_fma_f32 v[60:61], v[56:57], v[46:47], v[70:71] op_sel_hi:[1,0,1]
	s_waitcnt lgkmcnt(7)
; #define LAS __attribute__((address_space(3)))
; #define RW_LDS_WAIT(X) asm volatile("s_waitcnt lgkmcnt(0)" : "+v"(nk##X), "+v"(dd##X), "+v"(bb##X), "+v"(kp##X), "+v"(rr##X), "+v"(vv##X) :: "memory")
; DI void rwkv_scan_phase(int wv, const Params& P, LAS unsigned char* lds) {
;     ...
;                 f32x2 yacc = (f32x2){0.f, 0.f};
;                 unsigned sbt = sba, vbt = vba; LAS float* ybt = yb;
;                 RW_LDS_LOAD(A, 0); RW_LDS_WAIT(A);
; #pragma unroll 1
;                 for (int tt = 0; tt < RW_T; tt += 16) { sbt = sba + (unsigned)tt * 1280u; vbt = vba + (unsigned)tt * 32u; ybt = yb + tt * 128;
;                     RW_LDS_LOAD(B, 1); RW_STEP(A, 0); RW_LDS_WAIT(B);
;                     RW_LDS_LOAD(A, 2); RW_STEP(B, 1); RW_LDS_WAIT(A);
;                     RW_LDS_LOAD(B, 3); RW_STEP(A, 2); RW_LDS_WAIT(B);
;                     RW_LDS_LOAD(A, 4); RW_STEP(B, 3); RW_LDS_WAIT(A);
;                     RW_LDS_LOAD(B, 5); RW_STEP(A, 4); RW_LDS_WAIT(B);
;                     RW_LDS_LOAD(A, 6); RW_STEP(B, 5); RW_LDS_WAIT(A);
;                     RW_LDS_LOAD(B, 7); RW_STEP(A, 6); RW_LDS_WAIT(B);
;                     RW_LDS_LOAD(A, 8); RW_STEP(B, 7); RW_LDS_WAIT(A);
;                     RW_LDS_LOAD(B, 9); RW_STEP(A, 8); RW_LDS_WAIT(B);
;                     RW_LDS_LOAD(A, 10); RW_STEP(B, 9); RW_LDS_WAIT(A);
;                     RW_LDS_LOAD(B, 11); RW_STEP(A, 10); RW_LDS_WAIT(B);
;                     RW_LDS_LOAD(A, 12); RW_STEP(B, 11); RW_LDS_WAIT(A);
;                     RW_LDS_LOAD(B, 13); RW_STEP(A, 12); RW_LDS_WAIT(B);
;                     RW_LDS_LOAD(A, 14); RW_STEP(B, 13); RW_LDS_WAIT(A);
;                     RW_LDS_LOAD(B, 15); RW_STEP(A, 14); RW_LDS_WAIT(B);
;                     RW_LDS_LOAD(A, 16); RW_STEP(B, 15); RW_LDS_WAIT(A);
;                 }
;                 yb[(RW_T - 1) * 128] = yacc[0] + yacc[1];
;     ...
;                 __syncthreads();
	v_pk_mul_f32 v[0:1], v[58:59], v[0:1] op_sel_hi:[0,1]
	v_pk_fma_f32 v[0:1], v[58:59], v[2:3], v[0:1] op_sel:[1,0,0] op_sel_hi:[1,1,1]
	v_pk_fma_f32 v[0:1], v[60:61], v[16:17], v[0:1] op_sel_hi:[0,1,1]
	v_pk_fma_f32 v[0:1], v[60:61], v[18:19], v[0:1] op_sel:[1,0,0] op_sel_hi:[1,1,1]
	v_pk_fma_f32 v[12:13], v[58:59], v[4:5], v[12:13]
	v_pk_fma_f32 v[14:15], v[60:61], v[6:7], v[14:15]
	v_add_f32_dpp v0, v0, v0 quad_perm:[1,0,3,2] row_mask:0xf bank_mask:0xf bound_ctrl:1
	ds_read_b128 v[46:49], v74 offset:33792
	ds_read_b128 v[76:79], v74 offset:34048
	v_add_f32_dpp v0, v0, v0 quad_perm:[2,3,0,1] row_mask:0xf bank_mask:0xf bound_ctrl:1
	ds_read_b128 v[50:53], v74 offset:34304
	ds_read_b128 v[68:71], v75 offset:33792
	v_add_f32_dpp v0, v0, v0 row_half_mirror row_mask:0xf bank_mask:0xf bound_ctrl:1
	ds_read_b128 v[54:57], v74 offset:34560
	ds_write_b32 v72, v1 offset:4096
	v_add_f32_dpp v0, v0, v0 row_mirror row_mask:0xf bank_mask:0xf bound_ctrl:1
	v_pk_fma_f32 v[58:59], v[8:9], v[0:1], v[12:13] op_sel_hi:[1,0,1]
	v_pk_fma_f32 v[60:61], v[10:11], v[0:1], v[14:15] op_sel_hi:[1,0,1]
	s_waitcnt lgkmcnt(7)
	v_pk_mul_f32 v[20:21], v[58:59], v[20:21] op_sel_hi:[0,1]
	v_pk_fma_f32 v[20:21], v[58:59], v[22:23], v[20:21] op_sel:[1,0,0] op_sel_hi:[1,1,1]
	v_pk_fma_f32 v[20:21], v[60:61], v[36:37], v[20:21] op_sel_hi:[0,1,1]
	v_pk_fma_f32 v[20:21], v[60:61], v[38:39], v[20:21] op_sel:[1,0,0] op_sel_hi:[1,1,1]
	v_pk_fma_f32 v[32:33], v[58:59], v[24:25], v[32:33]
	v_pk_fma_f32 v[34:35], v[60:61], v[26:27], v[34:35]
	v_add_f32_dpp v20, v20, v20 quad_perm:[1,0,3,2] row_mask:0xf bank_mask:0xf bound_ctrl:1
	ds_read_b128 v[0:3], v74 offset:36864
	ds_read_b128 v[16:19], v74 offset:37120
	v_add_f32_dpp v20, v20, v20 quad_perm:[2,3,0,1] row_mask:0xf bank_mask:0xf bound_ctrl:1
	ds_read_b128 v[4:7], v74 offset:37376
	ds_read_b128 v[12:15], v75 offset:36864
	v_add_f32_dpp v20, v20, v20 row_half_mirror row_mask:0xf bank_mask:0xf bound_ctrl:1
	ds_read_b128 v[8:11], v74 offset:37632
	ds_write_b32 v72, v21 offset:4608
	v_add_f32_dpp v20, v20, v20 row_mirror row_mask:0xf bank_mask:0xf bound_ctrl:1
	v_pk_fma_f32 v[58:59], v[28:29], v[20:21], v[32:33] op_sel_hi:[1,0,1]
	v_pk_fma_f32 v[60:61], v[30:31], v[20:21], v[34:35] op_sel_hi:[1,0,1]
	s_waitcnt lgkmcnt(7)
	v_pk_mul_f32 v[46:47], v[58:59], v[46:47] op_sel_hi:[0,1]
	v_pk_fma_f32 v[46:47], v[58:59], v[48:49], v[46:47] op_sel:[1,0,0] op_sel_hi:[1,1,1]
	v_pk_fma_f32 v[46:47], v[60:61], v[76:77], v[46:47] op_sel_hi:[0,1,1]
	v_pk_fma_f32 v[46:47], v[60:61], v[78:79], v[46:47] op_sel:[1,0,0] op_sel_hi:[1,1,1]
	v_pk_fma_f32 v[68:69], v[58:59], v[50:51], v[68:69]
	v_pk_fma_f32 v[70:71], v[60:61], v[52:53], v[70:71]
	v_add_f32_dpp v46, v46, v46 quad_perm:[1,0,3,2] row_mask:0xf bank_mask:0xf bound_ctrl:1
	ds_read_b128 v[20:23], v74 offset:39936
	ds_read_b128 v[36:39], v74 offset:40192
	v_add_f32_dpp v46, v46, v46 quad_perm:[2,3,0,1] row_mask:0xf bank_mask:0xf bound_ctrl:1
	ds_read_b128 v[24:27], v74 offset:40448
	ds_read_b128 v[32:35], v75 offset:39936
	v_add_f32_dpp v46, v46, v46 row_half_mirror row_mask:0xf bank_mask:0xf bound_ctrl:1
	ds_read_b128 v[28:31], v74 offset:40704
	ds_write_b32 v72, v47 offset:5120
	v_add_f32_dpp v46, v46, v46 row_mirror row_mask:0xf bank_mask:0xf bound_ctrl:1
	v_pk_fma_f32 v[58:59], v[54:55], v[46:47], v[68:69] op_sel_hi:[1,0,1]
	v_pk_fma_f32 v[60:61], v[56:57], v[46:47], v[70:71] op_sel_hi:[1,0,1]
	s_waitcnt lgkmcnt(7)
	v_pk_mul_f32 v[0:1], v[58:59], v[0:1] op_sel_hi:[0,1]
	v_pk_fma_f32 v[0:1], v[58:59], v[2:3], v[0:1] op_sel:[1,0,0] op_sel_hi:[1,1,1]
	v_pk_fma_f32 v[0:1], v[60:61], v[16:17], v[0:1] op_sel_hi:[0,1,1]
	v_pk_fma_f32 v[0:1], v[60:61], v[18:19], v[0:1] op_sel:[1,0,0] op_sel_hi:[1,1,1]
	v_pk_fma_f32 v[12:13], v[58:59], v[4:5], v[12:13]
	v_pk_fma_f32 v[14:15], v[60:61], v[6:7], v[14:15]
	v_add_f32_dpp v0, v0, v0 quad_perm:[1,0,3,2] row_mask:0xf bank_mask:0xf bound_ctrl:1
	ds_read_b128 v[46:49], v74 offset:43008
	ds_read_b128 v[76:79], v74 offset:43264
	v_add_f32_dpp v0, v0, v0 quad_perm:[2,3,0,1] row_mask:0xf bank_mask:0xf bound_ctrl:1
	ds_read_b128 v[50:53], v74 offset:43520
	ds_read_b128 v[68:71], v75 offset:43008
	v_add_f32_dpp v0, v0, v0 row_half_mirror row_mask:0xf bank_mask:0xf bound_ctrl:1
	ds_read_b128 v[54:57], v74 offset:43776
	ds_write_b32 v72, v1 offset:5632
	v_add_f32_dpp v0, v0, v0 row_mirror row_mask:0xf bank_mask:0xf bound_ctrl:1
	v_pk_fma_f32 v[58:59], v[8:9], v[0:1], v[12:13] op_sel_hi:[1,0,1]
	v_pk_fma_f32 v[60:61], v[10:11], v[0:1], v[14:15] op_sel_hi:[1,0,1]
	s_waitcnt lgkmcnt(7)
	v_pk_mul_f32 v[20:21], v[58:59], v[20:21] op_sel_hi:[0,1]
	v_pk_fma_f32 v[20:21], v[58:59], v[22:23], v[20:21] op_sel:[1,0,0] op_sel_hi:[1,1,1]
	v_pk_fma_f32 v[20:21], v[60:61], v[36:37], v[20:21] op_sel_hi:[0,1,1]
	v_pk_fma_f32 v[20:21], v[60:61], v[38:39], v[20:21] op_sel:[1,0,0] op_sel_hi:[1,1,1]
	v_pk_fma_f32 v[32:33], v[58:59], v[24:25], v[32:33]
	v_pk_fma_f32 v[34:35], v[60:61], v[26:27], v[34:35]
	v_add_f32_dpp v20, v20, v20 quad_perm:[1,0,3,2] row_mask:0xf bank_mask:0xf bound_ctrl:1
	ds_read_b128 v[0:3], v74 offset:46080
	ds_read_b128 v[16:19], v74 offset:46336
	v_add_f32_dpp v20, v20, v20 quad_perm:[2,3,0,1] row_mask:0xf bank_mask:0xf bound_ctrl:1
	ds_read_b128 v[4:7], v74 offset:46592
	ds_read_b128 v[12:15], v75 offset:46080
	v_add_f32_dpp v20, v20, v20 row_half_mirror row_mask:0xf bank_mask:0xf bound_ctrl:1
	ds_read_b128 v[8:11], v74 offset:46848
	ds_write_b32 v72, v21 offset:6144
	v_add_f32_dpp v20, v20, v20 row_mirror row_mask:0xf bank_mask:0xf bound_ctrl:1
	v_pk_fma_f32 v[58:59], v[28:29], v[20:21], v[32:33] op_sel_hi:[1,0,1]
	v_pk_fma_f32 v[60:61], v[30:31], v[20:21], v[34:35] op_sel_hi:[1,0,1]
	s_waitcnt lgkmcnt(7)
	v_pk_mul_f32 v[46:47], v[58:59], v[46:47] op_sel_hi:[0,1]
	v_pk_fma_f32 v[46:47], v[58:59], v[48:49], v[46:47] op_sel:[1,0,0] op_sel_hi:[1,1,1]
	v_pk_fma_f32 v[46:47], v[60:61], v[76:77], v[46:47] op_sel_hi:[0,1,1]
	v_pk_fma_f32 v[46:47], v[60:61], v[78:79], v[46:47] op_sel:[1,0,0] op_sel_hi:[1,1,1]
	v_pk_fma_f32 v[68:69], v[58:59], v[50:51], v[68:69]
	v_pk_fma_f32 v[70:71], v[60:61], v[52:53], v[70:71]
	v_add_f32_dpp v46, v46, v46 quad_perm:[1,0,3,2] row_mask:0xf bank_mask:0xf bound_ctrl:1
	s_add_i32 s47, s47, 1
	ds_write_b32 v72, v47 offset:6656
	v_add_f32_dpp v46, v46, v46 quad_perm:[2,3,0,1] row_mask:0xf bank_mask:0xf bound_ctrl:1
	s_add_i32 s42, s42, 0x2000
	s_cmp_eq_u32 s42, 0x6000
	v_add_f32_dpp v46, v46, v46 row_half_mirror row_mask:0xf bank_mask:0xf bound_ctrl:1
	s_cselect_b32 s42, 0, s42
	v_add_u32_e32 v67, s42, v62
	v_add_f32_dpp v46, v46, v46 row_mirror row_mask:0xf bank_mask:0xf bound_ctrl:1
	v_pk_fma_f32 v[58:59], v[54:55], v[46:47], v[68:69] op_sel_hi:[1,0,1]
	v_pk_fma_f32 v[60:61], v[56:57], v[46:47], v[70:71] op_sel_hi:[1,0,1]
	s_waitcnt lgkmcnt(0)
	s_barrier
; #define RW_LDS_WAIT(X) asm volatile("s_waitcnt lgkmcnt(0)" : "+v"(nk##X), "+v"(dd##X), "+v"(bb##X), "+v"(kp##X), "+v"(rr##X), "+v"(vv##X) :: "memory")
; DI void rwkv_scan_phase(int wv, const Params& P, LAS unsigned char* lds) {
;     ...
;                 for (int tt = 0; tt < RW_T; tt += 16) { sbt = sba + (unsigned)tt * 1280u; vbt = vba + (unsigned)tt * 32u; ybt = yb + tt * 128;
;                     RW_LDS_LOAD(B, 1); RW_STEP(A, 0); RW_LDS_WAIT(B);
;                     RW_LDS_LOAD(A, 2); RW_STEP(B, 1); RW_LDS_WAIT(A);
;                     RW_LDS_LOAD(B, 3); RW_STEP(A, 2); RW_LDS_WAIT(B);
;                     RW_LDS_LOAD(A, 4); RW_STEP(B, 3); RW_LDS_WAIT(A);
;                     RW_LDS_LOAD(B, 5); RW_STEP(A, 4); RW_LDS_WAIT(B);
;                     RW_LDS_LOAD(A, 6); RW_STEP(B, 5); RW_LDS_WAIT(A);
;                     RW_LDS_LOAD(B, 7); RW_STEP(A, 6); RW_LDS_WAIT(B);
;                     RW_LDS_LOAD(A, 8); RW_STEP(B, 7); RW_LDS_WAIT(A);
;                     RW_LDS_LOAD(B, 9); RW_STEP(A, 8); RW_LDS_WAIT(B);
;                     RW_LDS_LOAD(A, 10); RW_STEP(B, 9); RW_LDS_WAIT(A);
;                     RW_LDS_LOAD(B, 11); RW_STEP(A, 10); RW_LDS_WAIT(B);
;                     RW_LDS_LOAD(A, 12); RW_STEP(B, 11); RW_LDS_WAIT(A);
;                     RW_LDS_LOAD(B, 13); RW_STEP(A, 12); RW_LDS_WAIT(B);
;                     RW_LDS_LOAD(A, 14); RW_STEP(B, 13); RW_LDS_WAIT(A);
;                     RW_LDS_LOAD(B, 15); RW_STEP(A, 14); RW_LDS_WAIT(B);
;                     RW_LDS_LOAD(A, 16); RW_STEP(B, 15); RW_LDS_WAIT(A);
;                 }
;                 yb[(RW_T - 1) * 128] = yacc[0] + yacc[1];
;     ...
;                 __syncthreads();
	v_pk_mul_f32 v[0:1], v[58:59], v[0:1] op_sel_hi:[0,1]
	v_pk_fma_f32 v[0:1], v[58:59], v[2:3], v[0:1] op_sel:[1,0,0] op_sel_hi:[1,1,1]
	v_pk_fma_f32 v[0:1], v[60:61], v[16:17], v[0:1] op_sel_hi:[0,1,1]
	v_pk_fma_f32 v[0:1], v[60:61], v[18:19], v[0:1] op_sel:[1,0,0] op_sel_hi:[1,1,1]
	v_pk_fma_f32 v[12:13], v[58:59], v[4:5], v[12:13]
	v_pk_fma_f32 v[14:15], v[60:61], v[6:7], v[14:15]
	v_add_f32_dpp v0, v0, v0 quad_perm:[1,0,3,2] row_mask:0xf bank_mask:0xf bound_ctrl:1
	ds_write_b32 v72, v1 offset:7168
	v_xor_b32_e32 v74, 0xc000, v74
	v_add_f32_dpp v0, v0, v0 quad_perm:[2,3,0,1] row_mask:0xf bank_mask:0xf bound_ctrl:1
	v_xor_b32_e32 v75, 0xc000, v75
	ds_read_b128 v[20:23], v74 offset:3072
	v_add_f32_dpp v0, v0, v0 row_half_mirror row_mask:0xf bank_mask:0xf bound_ctrl:1
	ds_read_b128 v[36:39], v74 offset:3328
	ds_read_b128 v[24:27], v74 offset:3584
	v_add_f32_dpp v0, v0, v0 row_mirror row_mask:0xf bank_mask:0xf bound_ctrl:1
	v_pk_fma_f32 v[58:59], v[8:9], v[0:1], v[12:13] op_sel_hi:[1,0,1]
	v_pk_fma_f32 v[60:61], v[10:11], v[0:1], v[14:15] op_sel_hi:[1,0,1]
	s_cmpk_eq_i32 s47, 0x200
	ds_read_b128 v[0:3], v74
	ds_read_b128 v[16:19], v74 offset:256
	ds_read_b128 v[4:7], v74 offset:512
	ds_read_b128 v[12:15], v75
	ds_read_b128 v[8:11], v74 offset:768
	ds_read_b128 v[32:35], v75 offset:3072
	ds_read_b128 v[28:31], v74 offset:3840
	s_cbranch_scc0 .Lscan_chunk
	v_add_u32_e32 v40, 0x1e100, v45
	ds_read_b128 v[20:23], v40
	s_waitcnt lgkmcnt(0)
	v_pk_mul_f32 v[64:65], v[20:21], v[58:59]
	v_pk_fma_f32 v[64:65], v[22:23], v[60:61], v[64:65]
	s_nop 0
	v_add_f32_e32 v64, v64, v65
	ds_write_b32 v72, v64 offset:7680
	s_waitcnt lgkmcnt(0)
	s_barrier
